# code placement: the eight GEMM K-loop heads and the two attention loop heads aligned to 64 bytes (s_nop fill)
# baseline (speedup 1.0000x reference)
; template <class Epi>
; DI void gemm_phase(const int TID, const int BID, LAS unsigned char* lds, const Gemm g, const Epi& E) {
;     ...
;         for (int t = 0; t < nt; t += 2) {
;             const bool last = (t == nt - 2);
;             const char* a1 = cA + (size_t)(t + 1) * kstep;
;             const char* a2 = last ? nA : cA + (size_t)(t + 2) * kstep; const char* b2 = last ? nB : cB + (size_t)(t + 2) * kstep;
;             const char* a3 = a2 + kstep; const char* b3 = b2 + kstep;
;     ...
;         if (!has_next) break;
; #pragma unroll
;         for (int a = 0; a < 2; ++a)
; #pragma unroll
;             for (int b = 0; b < 2; ++b)
; #pragma unroll
;                 for (int m = 0; m < 4; ++m)
; #pragma unroll
;                     for (int n = 0; n < 2; ++n) acc[a][b][m][n] = (f32x4){0.f, 0.f, 0.f, 0.f};
;         cur = nxt; cA = nA; cB = nB; ++ui;
.LBB0_136:
	s_add_i32 vcc_lo, s5, -2
	s_add_u32 s56, s56, 0x80
	s_addc_u32 s57, s57, 0
	s_add_u32 vcc_hi, s58, 0x100
	v_mov_b32_e32 v0, 0
	s_addc_u32 s18, s59, 0
	s_mov_b32 s58, 0
	v_mov_b32_e32 v1, v0
	v_mov_b32_e32 v2, v0
	v_mov_b32_e32 v3, v0
	v_mov_b32_e32 v4, v0
	v_mov_b32_e32 v5, v0
	v_mov_b32_e32 v6, v0
	v_mov_b32_e32 v7, v0
	v_mov_b32_e32 v16, v0
	v_mov_b32_e32 v17, v0
	v_mov_b32_e32 v18, v0
	v_mov_b32_e32 v19, v0
	v_mov_b32_e32 v20, v0
	v_mov_b32_e32 v21, v0
	v_mov_b32_e32 v22, v0
	v_mov_b32_e32 v23, v0
	v_mov_b32_e32 v32, v0
	v_mov_b32_e32 v33, v0
	v_mov_b32_e32 v34, v0
	v_mov_b32_e32 v35, v0
	v_mov_b32_e32 v36, v0
	v_mov_b32_e32 v37, v0
	v_mov_b32_e32 v38, v0
	v_mov_b32_e32 v39, v0
	v_mov_b32_e32 v48, v0
	v_mov_b32_e32 v49, v0
	v_mov_b32_e32 v50, v0
	v_mov_b32_e32 v51, v0
	v_mov_b32_e32 v52, v0
	v_mov_b32_e32 v53, v0
	v_mov_b32_e32 v54, v0
	v_mov_b32_e32 v55, v0
	v_mov_b32_e32 v8, v0
	v_mov_b32_e32 v9, v0
	v_mov_b32_e32 v10, v0
	v_mov_b32_e32 v11, v0
	v_mov_b32_e32 v12, v0
	v_mov_b32_e32 v13, v0
	v_mov_b32_e32 v14, v0
	v_mov_b32_e32 v15, v0
	v_mov_b32_e32 v24, v0
	v_mov_b32_e32 v25, v0
	v_mov_b32_e32 v26, v0
	v_mov_b32_e32 v27, v0
	v_mov_b32_e32 v28, v0
	v_mov_b32_e32 v29, v0
	v_mov_b32_e32 v30, v0
	v_mov_b32_e32 v31, v0
	v_mov_b32_e32 v40, v0
	v_mov_b32_e32 v41, v0
	v_mov_b32_e32 v42, v0
	v_mov_b32_e32 v43, v0
	v_mov_b32_e32 v44, v0
	v_mov_b32_e32 v45, v0
	v_mov_b32_e32 v46, v0
	v_mov_b32_e32 v47, v0
	v_mov_b32_e32 v56, v0
	v_mov_b32_e32 v57, v0
	v_mov_b32_e32 v58, v0
	v_mov_b32_e32 v59, v0
	v_mov_b32_e32 v60, v0
	v_mov_b32_e32 v61, v0
	v_mov_b32_e32 v62, v0
	v_mov_b32_e32 v63, v0
	v_mov_b32_e32 v64, v0
	v_mov_b32_e32 v65, v0
	v_mov_b32_e32 v66, v0
	v_mov_b32_e32 v67, v0
	v_mov_b32_e32 v68, v0
	v_mov_b32_e32 v69, v0
	v_mov_b32_e32 v70, v0
	v_mov_b32_e32 v71, v0
	v_mov_b32_e32 v80, v0
	v_mov_b32_e32 v81, v0
	v_mov_b32_e32 v82, v0
	v_mov_b32_e32 v83, v0
	v_mov_b32_e32 v84, v0
	v_mov_b32_e32 v85, v0
	v_mov_b32_e32 v86, v0
	v_mov_b32_e32 v87, v0
	v_mov_b32_e32 v96, v0
	v_mov_b32_e32 v97, v0
	v_mov_b32_e32 v98, v0
	v_mov_b32_e32 v99, v0
	v_mov_b32_e32 v100, v0
	v_mov_b32_e32 v101, v0
	v_mov_b32_e32 v102, v0
	v_mov_b32_e32 v103, v0
	v_mov_b32_e32 v112, v0
	v_mov_b32_e32 v113, v0
	v_mov_b32_e32 v114, v0
	v_mov_b32_e32 v115, v0
	v_mov_b32_e32 v116, v0
	v_mov_b32_e32 v117, v0
	v_mov_b32_e32 v118, v0
	v_mov_b32_e32 v119, v0
	v_mov_b32_e32 v72, v0
	v_mov_b32_e32 v73, v0
	v_mov_b32_e32 v74, v0
	v_mov_b32_e32 v75, v0
	v_mov_b32_e32 v76, v0
	v_mov_b32_e32 v77, v0
	v_mov_b32_e32 v78, v0
	v_mov_b32_e32 v79, v0
	v_mov_b32_e32 v88, v0
	v_mov_b32_e32 v89, v0
	v_mov_b32_e32 v90, v0
	v_mov_b32_e32 v91, v0
	v_mov_b32_e32 v92, v0
	v_mov_b32_e32 v93, v0
	v_mov_b32_e32 v94, v0
	v_mov_b32_e32 v95, v0
	v_mov_b32_e32 v104, v0
	v_mov_b32_e32 v105, v0
	v_mov_b32_e32 v106, v0
	v_mov_b32_e32 v107, v0
	v_mov_b32_e32 v108, v0
	v_mov_b32_e32 v109, v0
	v_mov_b32_e32 v110, v0
	v_mov_b32_e32 v111, v0
	v_mov_b32_e32 v120, v0
	v_mov_b32_e32 v121, v0
	v_mov_b32_e32 v122, v0
	v_mov_b32_e32 v123, v0
	v_mov_b32_e32 v124, v0
	v_mov_b32_e32 v125, v0
	v_mov_b32_e32 v126, v0
	v_mov_b32_e32 v127, v0
	.p2alignl 6, 3212836864

; template <class Epi>
; DI void gemm_phase(const int TID, const int BID, LAS unsigned char* lds, const Gemm g, const Epi& E) {
;     ...
;         if (!has_next) break;
; #pragma unroll
;         for (int a = 0; a < 2; ++a)
; #pragma unroll
;             for (int b = 0; b < 2; ++b)
; #pragma unroll
;                 for (int m = 0; m < 4; ++m)
; #pragma unroll
;                     for (int n = 0; n < 2; ++n) acc[a][b][m][n] = (f32x4){0.f, 0.f, 0.f, 0.f};
;         cur = nxt; cA = nA; cB = nB; ++ui;
.LBB0_162:
	v_mov_b32_e32 v127, 0
	s_andn2_b64 vcc, exec, s[8:9]
	v_mov_b32_e32 v126, v127
	v_mov_b32_e32 v125, v127
	v_mov_b32_e32 v124, v127
	v_mov_b32_e32 v123, v127
	v_mov_b32_e32 v122, v127
	v_mov_b32_e32 v121, v127
	v_mov_b32_e32 v120, v127
	v_mov_b32_e32 v111, v127
	v_mov_b32_e32 v110, v127
	v_mov_b32_e32 v109, v127
	v_mov_b32_e32 v108, v127
	v_mov_b32_e32 v107, v127
	v_mov_b32_e32 v106, v127
	v_mov_b32_e32 v105, v127
	v_mov_b32_e32 v104, v127
	v_mov_b32_e32 v95, v127
	v_mov_b32_e32 v94, v127
	v_mov_b32_e32 v93, v127
	v_mov_b32_e32 v92, v127
	v_mov_b32_e32 v91, v127
	v_mov_b32_e32 v90, v127
	v_mov_b32_e32 v89, v127
	v_mov_b32_e32 v88, v127
	v_mov_b32_e32 v79, v127
	v_mov_b32_e32 v78, v127
	v_mov_b32_e32 v77, v127
	v_mov_b32_e32 v76, v127
	v_mov_b32_e32 v75, v127
	v_mov_b32_e32 v74, v127
	v_mov_b32_e32 v73, v127
	v_mov_b32_e32 v72, v127
	v_mov_b32_e32 v119, v127
	v_mov_b32_e32 v118, v127
	v_mov_b32_e32 v117, v127
	v_mov_b32_e32 v116, v127
	v_mov_b32_e32 v115, v127
	v_mov_b32_e32 v114, v127
	v_mov_b32_e32 v113, v127
	v_mov_b32_e32 v112, v127
	v_mov_b32_e32 v103, v127
	v_mov_b32_e32 v102, v127
	v_mov_b32_e32 v101, v127
	v_mov_b32_e32 v100, v127
	v_mov_b32_e32 v99, v127
	v_mov_b32_e32 v98, v127
	v_mov_b32_e32 v97, v127
	v_mov_b32_e32 v96, v127
	v_mov_b32_e32 v87, v127
	v_mov_b32_e32 v86, v127
	v_mov_b32_e32 v85, v127
	v_mov_b32_e32 v84, v127
	v_mov_b32_e32 v83, v127
	v_mov_b32_e32 v82, v127
	v_mov_b32_e32 v81, v127
	v_mov_b32_e32 v80, v127
	v_mov_b32_e32 v71, v127
	v_mov_b32_e32 v70, v127
	v_mov_b32_e32 v69, v127
	v_mov_b32_e32 v68, v127
	v_mov_b32_e32 v67, v127
	v_mov_b32_e32 v66, v127
	v_mov_b32_e32 v65, v127
	v_mov_b32_e32 v64, v127
	v_mov_b32_e32 v63, v127
	v_mov_b32_e32 v62, v127
	v_mov_b32_e32 v61, v127
	v_mov_b32_e32 v60, v127
	v_mov_b32_e32 v59, v127
	v_mov_b32_e32 v58, v127
	v_mov_b32_e32 v57, v127
	v_mov_b32_e32 v56, v127
	v_mov_b32_e32 v47, v127
	v_mov_b32_e32 v46, v127
	v_mov_b32_e32 v45, v127
	v_mov_b32_e32 v44, v127
	v_mov_b32_e32 v43, v127
	v_mov_b32_e32 v42, v127
	v_mov_b32_e32 v41, v127
	v_mov_b32_e32 v40, v127
	v_mov_b32_e32 v31, v127
	v_mov_b32_e32 v30, v127
	v_mov_b32_e32 v29, v127
	v_mov_b32_e32 v28, v127
	v_mov_b32_e32 v27, v127
	v_mov_b32_e32 v26, v127
	v_mov_b32_e32 v25, v127
	v_mov_b32_e32 v24, v127
	v_mov_b32_e32 v15, v127
	v_mov_b32_e32 v14, v127
	v_mov_b32_e32 v13, v127
	v_mov_b32_e32 v12, v127
	v_mov_b32_e32 v11, v127
	v_mov_b32_e32 v10, v127
	v_mov_b32_e32 v9, v127
	v_mov_b32_e32 v8, v127
	v_mov_b32_e32 v55, v127
	v_mov_b32_e32 v54, v127
	v_mov_b32_e32 v53, v127
	v_mov_b32_e32 v52, v127
	v_mov_b32_e32 v51, v127
	v_mov_b32_e32 v50, v127
	v_mov_b32_e32 v49, v127
	v_mov_b32_e32 v48, v127
	v_mov_b32_e32 v39, v127
	v_mov_b32_e32 v38, v127
	v_mov_b32_e32 v37, v127
	v_mov_b32_e32 v36, v127
	v_mov_b32_e32 v35, v127
	v_mov_b32_e32 v34, v127
	v_mov_b32_e32 v33, v127
	v_mov_b32_e32 v32, v127
	v_mov_b32_e32 v23, v127
	v_mov_b32_e32 v22, v127
	v_mov_b32_e32 v21, v127
	v_mov_b32_e32 v20, v127
	v_mov_b32_e32 v19, v127
	v_mov_b32_e32 v18, v127
	v_mov_b32_e32 v17, v127
	v_mov_b32_e32 v16, v127
	v_mov_b32_e32 v7, v127
	v_mov_b32_e32 v6, v127
	v_mov_b32_e32 v5, v127
	v_mov_b32_e32 v4, v127
	v_mov_b32_e32 v3, v127
	v_mov_b32_e32 v2, v127
	v_mov_b32_e32 v1, v127
	v_mov_b32_e32 v0, v127
	s_cbranch_vccnz .LBB0_155
	s_add_u32 s54, s54, 0x80
	s_addc_u32 s55, s55, 0
	s_add_u32 s76, s56, 0x100
	s_addc_u32 s77, s57, 0
	s_mov_b32 s56, 0
	.p2alignl 6, 3212836864

; template <class Epi>
; DI void gemm_phase(const int TID, const int BID, LAS unsigned char* lds, const Gemm g, const Epi& E) {
;     ...
;         for (int t = 0; t < nt; t += 2) {
;             const bool last = (t == nt - 2);
;             const char* a1 = cA + (size_t)(t + 1) * kstep;
;             const char* a2 = last ? nA : cA + (size_t)(t + 2) * kstep; const char* b2 = last ? nB : cB + (size_t)(t + 2) * kstep;
;             const char* a3 = a2 + kstep; const char* b3 = b2 + kstep;
;     ...
;         if (!has_next) break;
; #pragma unroll
;         for (int a = 0; a < 2; ++a)
; #pragma unroll
;             for (int b = 0; b < 2; ++b)
; #pragma unroll
;                 for (int m = 0; m < 4; ++m)
; #pragma unroll
;                     for (int n = 0; n < 2; ++n) acc[a][b][m][n] = (f32x4){0.f, 0.f, 0.f, 0.f};
;         cur = nxt; cA = nA; cB = nB; ++ui;
.LBB0_229:
	s_add_i32 vcc_lo, s17, -2
	s_add_u32 s52, s52, 0x80
	s_addc_u32 s53, s53, 0
	s_add_u32 vcc_hi, s54, 0x100
	v_mov_b32_e32 v0, 0
	s_addc_u32 s29, s55, 0
	s_mov_b32 s54, 0
	v_mov_b32_e32 v1, v0
	v_mov_b32_e32 v2, v0
	v_mov_b32_e32 v3, v0
	v_mov_b32_e32 v4, v0
	v_mov_b32_e32 v5, v0
	v_mov_b32_e32 v6, v0
	v_mov_b32_e32 v7, v0
	v_mov_b32_e32 v16, v0
	v_mov_b32_e32 v17, v0
	v_mov_b32_e32 v18, v0
	v_mov_b32_e32 v19, v0
	v_mov_b32_e32 v20, v0
	v_mov_b32_e32 v21, v0
	v_mov_b32_e32 v22, v0
	v_mov_b32_e32 v23, v0
	v_mov_b32_e32 v32, v0
	v_mov_b32_e32 v33, v0
	v_mov_b32_e32 v34, v0
	v_mov_b32_e32 v35, v0
	v_mov_b32_e32 v36, v0
	v_mov_b32_e32 v37, v0
	v_mov_b32_e32 v38, v0
	v_mov_b32_e32 v39, v0
	v_mov_b32_e32 v48, v0
	v_mov_b32_e32 v49, v0
	v_mov_b32_e32 v50, v0
	v_mov_b32_e32 v51, v0
	v_mov_b32_e32 v52, v0
	v_mov_b32_e32 v53, v0
	v_mov_b32_e32 v54, v0
	v_mov_b32_e32 v55, v0
	v_mov_b32_e32 v8, v0
	v_mov_b32_e32 v9, v0
	v_mov_b32_e32 v10, v0
	v_mov_b32_e32 v11, v0
	v_mov_b32_e32 v12, v0
	v_mov_b32_e32 v13, v0
	v_mov_b32_e32 v14, v0
	v_mov_b32_e32 v15, v0
	v_mov_b32_e32 v24, v0
	v_mov_b32_e32 v25, v0
	v_mov_b32_e32 v26, v0
	v_mov_b32_e32 v27, v0
	v_mov_b32_e32 v28, v0
	v_mov_b32_e32 v29, v0
	v_mov_b32_e32 v30, v0
	v_mov_b32_e32 v31, v0
	v_mov_b32_e32 v40, v0
	v_mov_b32_e32 v41, v0
	v_mov_b32_e32 v42, v0
	v_mov_b32_e32 v43, v0
	v_mov_b32_e32 v44, v0
	v_mov_b32_e32 v45, v0
	v_mov_b32_e32 v46, v0
	v_mov_b32_e32 v47, v0
	v_mov_b32_e32 v56, v0
	v_mov_b32_e32 v57, v0
	v_mov_b32_e32 v58, v0
	v_mov_b32_e32 v59, v0
	v_mov_b32_e32 v60, v0
	v_mov_b32_e32 v61, v0
	v_mov_b32_e32 v62, v0
	v_mov_b32_e32 v63, v0
	v_mov_b32_e32 v64, v0
	v_mov_b32_e32 v65, v0
	v_mov_b32_e32 v66, v0
	v_mov_b32_e32 v67, v0
	v_mov_b32_e32 v68, v0
	v_mov_b32_e32 v69, v0
	v_mov_b32_e32 v70, v0
	v_mov_b32_e32 v71, v0
	v_mov_b32_e32 v80, v0
	v_mov_b32_e32 v81, v0
	v_mov_b32_e32 v82, v0
	v_mov_b32_e32 v83, v0
	v_mov_b32_e32 v84, v0
	v_mov_b32_e32 v85, v0
	v_mov_b32_e32 v86, v0
	v_mov_b32_e32 v87, v0
	v_mov_b32_e32 v96, v0
	v_mov_b32_e32 v97, v0
	v_mov_b32_e32 v98, v0
	v_mov_b32_e32 v99, v0
	v_mov_b32_e32 v100, v0
	v_mov_b32_e32 v101, v0
	v_mov_b32_e32 v102, v0
	v_mov_b32_e32 v103, v0
	v_mov_b32_e32 v112, v0
	v_mov_b32_e32 v113, v0
	v_mov_b32_e32 v114, v0
	v_mov_b32_e32 v115, v0
	v_mov_b32_e32 v116, v0
	v_mov_b32_e32 v117, v0
	v_mov_b32_e32 v118, v0
	v_mov_b32_e32 v119, v0
	v_mov_b32_e32 v72, v0
	v_mov_b32_e32 v73, v0
	v_mov_b32_e32 v74, v0
	v_mov_b32_e32 v75, v0
	v_mov_b32_e32 v76, v0
	v_mov_b32_e32 v77, v0
	v_mov_b32_e32 v78, v0
	v_mov_b32_e32 v79, v0
	v_mov_b32_e32 v88, v0
	v_mov_b32_e32 v89, v0
	v_mov_b32_e32 v90, v0
	v_mov_b32_e32 v91, v0
	v_mov_b32_e32 v92, v0
	v_mov_b32_e32 v93, v0
	v_mov_b32_e32 v94, v0
	v_mov_b32_e32 v95, v0
	v_mov_b32_e32 v104, v0
	v_mov_b32_e32 v105, v0
	v_mov_b32_e32 v106, v0
	v_mov_b32_e32 v107, v0
	v_mov_b32_e32 v108, v0
	v_mov_b32_e32 v109, v0
	v_mov_b32_e32 v110, v0
	v_mov_b32_e32 v111, v0
	v_mov_b32_e32 v120, v0
	v_mov_b32_e32 v121, v0
	v_mov_b32_e32 v122, v0
	v_mov_b32_e32 v123, v0
	v_mov_b32_e32 v124, v0
	v_mov_b32_e32 v125, v0
	v_mov_b32_e32 v126, v0
	v_mov_b32_e32 v127, v0
	.p2alignl 6, 3212836864

; template <class Epi>
; DI void gemm_phase(const int TID, const int BID, LAS unsigned char* lds, const Gemm g, const Epi& E) {
;     ...
;         for (int t = 0; t < nt; t += 2) {
;             const bool last = (t == nt - 2);
;             const char* a1 = cA + (size_t)(t + 1) * kstep;
;             const char* a2 = last ? nA : cA + (size_t)(t + 2) * kstep; const char* b2 = last ? nB : cB + (size_t)(t + 2) * kstep;
;             const char* a3 = a2 + kstep; const char* b3 = b2 + kstep;
;     ...
;         if (!has_next) break;
; #pragma unroll
;         for (int a = 0; a < 2; ++a)
; #pragma unroll
;             for (int b = 0; b < 2; ++b)
; #pragma unroll
;                 for (int m = 0; m < 4; ++m)
; #pragma unroll
;                     for (int n = 0; n < 2; ++n) acc[a][b][m][n] = (f32x4){0.f, 0.f, 0.f, 0.f};
;         cur = nxt; cA = nA; cB = nB; ++ui;
.LBB0_270:
	s_add_i32 s54, s80, -2
	s_add_u32 s0, s52, 0x80
	s_addc_u32 s1, s53, 0
	s_add_u32 s55, s12, 0x100
	v_mov_b32_e32 v0, 0
	s_addc_u32 vcc_lo, s13, 0
	s_mov_b32 s12, 0
	v_mov_b32_e32 v1, v0
	v_mov_b32_e32 v2, v0
	v_mov_b32_e32 v3, v0
	v_mov_b32_e32 v4, v0
	v_mov_b32_e32 v5, v0
	v_mov_b32_e32 v6, v0
	v_mov_b32_e32 v7, v0
	v_mov_b32_e32 v16, v0
	v_mov_b32_e32 v17, v0
	v_mov_b32_e32 v18, v0
	v_mov_b32_e32 v19, v0
	v_mov_b32_e32 v20, v0
	v_mov_b32_e32 v21, v0
	v_mov_b32_e32 v22, v0
	v_mov_b32_e32 v23, v0
	v_mov_b32_e32 v32, v0
	v_mov_b32_e32 v33, v0
	v_mov_b32_e32 v34, v0
	v_mov_b32_e32 v35, v0
	v_mov_b32_e32 v36, v0
	v_mov_b32_e32 v37, v0
	v_mov_b32_e32 v38, v0
	v_mov_b32_e32 v39, v0
	v_mov_b32_e32 v48, v0
	v_mov_b32_e32 v49, v0
	v_mov_b32_e32 v50, v0
	v_mov_b32_e32 v51, v0
	v_mov_b32_e32 v52, v0
	v_mov_b32_e32 v53, v0
	v_mov_b32_e32 v54, v0
	v_mov_b32_e32 v55, v0
	v_mov_b32_e32 v8, v0
	v_mov_b32_e32 v9, v0
	v_mov_b32_e32 v10, v0
	v_mov_b32_e32 v11, v0
	v_mov_b32_e32 v12, v0
	v_mov_b32_e32 v13, v0
	v_mov_b32_e32 v14, v0
	v_mov_b32_e32 v15, v0
	v_mov_b32_e32 v24, v0
	v_mov_b32_e32 v25, v0
	v_mov_b32_e32 v26, v0
	v_mov_b32_e32 v27, v0
	v_mov_b32_e32 v28, v0
	v_mov_b32_e32 v29, v0
	v_mov_b32_e32 v30, v0
	v_mov_b32_e32 v31, v0
	v_mov_b32_e32 v40, v0
	v_mov_b32_e32 v41, v0
	v_mov_b32_e32 v42, v0
	v_mov_b32_e32 v43, v0
	v_mov_b32_e32 v44, v0
	v_mov_b32_e32 v45, v0
	v_mov_b32_e32 v46, v0
	v_mov_b32_e32 v47, v0
	v_mov_b32_e32 v56, v0
	v_mov_b32_e32 v57, v0
	v_mov_b32_e32 v58, v0
	v_mov_b32_e32 v59, v0
	v_mov_b32_e32 v60, v0
	v_mov_b32_e32 v61, v0
	v_mov_b32_e32 v62, v0
	v_mov_b32_e32 v63, v0
	v_mov_b32_e32 v64, v0
	v_mov_b32_e32 v65, v0
	v_mov_b32_e32 v66, v0
	v_mov_b32_e32 v67, v0
	v_mov_b32_e32 v68, v0
	v_mov_b32_e32 v69, v0
	v_mov_b32_e32 v70, v0
	v_mov_b32_e32 v71, v0
	v_mov_b32_e32 v80, v0
	v_mov_b32_e32 v81, v0
	v_mov_b32_e32 v82, v0
	v_mov_b32_e32 v83, v0
	v_mov_b32_e32 v84, v0
	v_mov_b32_e32 v85, v0
	v_mov_b32_e32 v86, v0
	v_mov_b32_e32 v87, v0
	v_mov_b32_e32 v96, v0
	v_mov_b32_e32 v97, v0
	v_mov_b32_e32 v98, v0
	v_mov_b32_e32 v99, v0
	v_mov_b32_e32 v100, v0
	v_mov_b32_e32 v101, v0
	v_mov_b32_e32 v102, v0
	v_mov_b32_e32 v103, v0
	v_mov_b32_e32 v112, v0
	v_mov_b32_e32 v113, v0
	v_mov_b32_e32 v114, v0
	v_mov_b32_e32 v115, v0
	v_mov_b32_e32 v116, v0
	v_mov_b32_e32 v117, v0
	v_mov_b32_e32 v118, v0
	v_mov_b32_e32 v119, v0
	v_mov_b32_e32 v72, v0
	v_mov_b32_e32 v73, v0
	v_mov_b32_e32 v74, v0
	v_mov_b32_e32 v75, v0
	v_mov_b32_e32 v76, v0
	v_mov_b32_e32 v77, v0
	v_mov_b32_e32 v78, v0
	v_mov_b32_e32 v79, v0
	v_mov_b32_e32 v88, v0
	v_mov_b32_e32 v89, v0
	v_mov_b32_e32 v90, v0
	v_mov_b32_e32 v91, v0
	v_mov_b32_e32 v92, v0
	v_mov_b32_e32 v93, v0
	v_mov_b32_e32 v94, v0
	v_mov_b32_e32 v95, v0
	v_mov_b32_e32 v104, v0
	v_mov_b32_e32 v105, v0
	v_mov_b32_e32 v106, v0
	v_mov_b32_e32 v107, v0
	v_mov_b32_e32 v108, v0
	v_mov_b32_e32 v109, v0
	v_mov_b32_e32 v110, v0
	v_mov_b32_e32 v111, v0
	v_mov_b32_e32 v120, v0
	v_mov_b32_e32 v121, v0
	v_mov_b32_e32 v122, v0
	v_mov_b32_e32 v123, v0
	v_mov_b32_e32 v124, v0
	v_mov_b32_e32 v125, v0
	v_mov_b32_e32 v126, v0
	v_mov_b32_e32 v127, v0
	.p2alignl 6, 3212836864

; #define AT_GLOADK(k0) do { kreg = *(const u32x4*)(Kb + (size_t)((k0) + (tid >> 3)) * 64 + (tid & 7) * 8); \
;             if (MLA) preg = *(const u32x2*)(Pb + (size_t)((k0) + (tid >> 3)) * 32 + (tid & 7) * 4); } while (0)
; #define AT_GLOADV(k0) do { vreg = *(const u32x4*)(Vb + (size_t)((k0) + (tid >> 3)) * 64 + (tid & 7) * 8); } while (0)
; #define AT_WRITEK(buf) do { *(LAS u32x4*)(lds + (buf) * KBUF + (tid >> 3) * KSTR + (tid & 7) * 16) = kreg; \
;             if (MLA) *(LAS u32x2*)(lds + (buf) * KBUF + (tid >> 3) * KSTR + 128 + (tid & 7) * 8) = preg; } while (0)
; #define AT_WRITEV(buf) do { *(LAS u32x4*)(lds + 2 * KBUF + (buf) * VBUF + (tid >> 3) * VSTR + (tid & 7) * 16) = vreg; } while (0)
; template <bool MLA>
; DI void attn_phase(const int TID, const int BID, LAS unsigned char* lds, const Params& p, bool need_ctx) {
;     ...
;         AT_GLOADK(0); AT_GLOADV(0); AT_WRITEK(0); AT_WRITEV(0);
;         AT_GLOADK(64); AT_WRITEK(1);
;         __syncthreads();
;         AT_QK(sa0, sa1, 0);
;         __syncthreads();
.Lamla_prio:
	ds_read_b128 v[136:139], v243 offset:0
	ds_read_b128 v[140:143], v243 offset:6656
	ds_read_b128 v[144:147], v243 offset:32
	ds_read_b128 v[148:151], v243 offset:6688
	s_waitcnt lgkmcnt(3)
	v_mfma_f32_32x32x16_bf16 v[32:47], v[136:139], v[112:115], 0
	ds_read_b128 v[136:139], v243 offset:64
	s_waitcnt lgkmcnt(3)
	v_mfma_f32_32x32x16_bf16 v[48:63], v[140:143], v[112:115], 0
	ds_read_b128 v[140:143], v243 offset:6720
	s_waitcnt lgkmcnt(3)
	v_mfma_f32_32x32x16_bf16 v[32:47], v[144:147], v[116:119], v[32:47]
	ds_read_b128 v[144:147], v243 offset:96
	s_waitcnt lgkmcnt(3)
	v_mfma_f32_32x32x16_bf16 v[48:63], v[148:151], v[116:119], v[48:63]
	ds_read_b128 v[148:151], v243 offset:6752
	s_waitcnt lgkmcnt(3)
	v_mfma_f32_32x32x16_bf16 v[32:47], v[136:139], v[120:123], v[32:47]
	ds_read_b128 v[136:139], v243 offset:128
	s_waitcnt lgkmcnt(3)
	v_mfma_f32_32x32x16_bf16 v[48:63], v[140:143], v[120:123], v[48:63]
	ds_read_b128 v[140:143], v243 offset:6784
	s_waitcnt lgkmcnt(3)
	v_mfma_f32_32x32x16_bf16 v[32:47], v[144:147], v[124:127], v[32:47]
	ds_read_b128 v[144:147], v243 offset:160
	s_waitcnt lgkmcnt(3)
	v_mfma_f32_32x32x16_bf16 v[48:63], v[148:151], v[124:127], v[48:63]
	ds_read_b128 v[148:151], v243 offset:6816
	s_waitcnt lgkmcnt(3)
	v_mfma_f32_32x32x16_bf16 v[32:47], v[136:139], v[128:131], v[32:47]
	s_waitcnt lgkmcnt(2)
	v_mfma_f32_32x32x16_bf16 v[48:63], v[140:143], v[128:131], v[48:63]
	s_waitcnt lgkmcnt(1)
	v_mfma_f32_32x32x16_bf16 v[32:47], v[144:147], v[132:135], v[32:47]
	s_waitcnt lgkmcnt(0)
	v_mfma_f32_32x32x16_bf16 v[48:63], v[148:151], v[132:135], v[48:63]
	s_waitcnt lgkmcnt(0)
	s_nop 7
	s_barrier
; #define AT_STEP(SC0, SC1, SN0, SN1, t, DOK, DOV) do { \
;             if (DOK) AT_GLOADK(((t) + 2) * 64); \
;             if (DOV) { AT_GLOADV(((t) + 1) * 64); AT_QK(SN0, SN1, ((t) + 1) & 1); } \
;             AT_SMPV(SC0, SC1, (t) & 1); \
;             if (DOK) AT_WRITEK((t) & 1); \
;             if (DOV) AT_WRITEV(((t) + 1) & 1); \
;             __syncthreads(); } while (0)
; template <bool MLA>
; DI void attn_phase(const int TID, const int BID, LAS unsigned char* lds, const Params& p, bool need_ctx) {
;     ...
;         AT_QK(sa0, sa1, 0);
;         __syncthreads();
;         int t = 0;
;         for (; t < ntile - 2; t += 2) {
;             AT_STEP(sa0, sa1, sb0, sb1, t, true, true);
;             AT_STEP(sb0, sb1, sa0, sa1, t + 1, true, true);
;         }
	ds_read_b128 v[136:139], v243 offset:13312
	ds_read_b128 v[140:143], v243 offset:19968
	ds_read_b128 v[144:147], v243 offset:13344
	ds_read_b128 v[148:151], v243 offset:20000
	v_max3_f32 v168, v32, v33, v34
	v_max3_f32 v170, v48, v49, v50
	v_max3_f32 v168, v168, v35, v36
	v_max3_f32 v170, v170, v51, v52
	v_max3_f32 v168, v168, v37, v38
	v_max3_f32 v170, v170, v53, v54
	v_max3_f32 v168, v168, v39, v40
	v_max3_f32 v170, v170, v55, v56
	v_max3_f32 v168, v168, v41, v42
	v_max3_f32 v170, v170, v57, v58
	v_max3_f32 v168, v168, v43, v44
	v_max3_f32 v170, v170, v59, v60
	v_max3_f32 v168, v168, v45, v46
	v_max3_f32 v170, v170, v61, v62
	v_max_f32_e32 v168, v168, v47
	v_max_f32_e32 v170, v170, v63
	v_max_f32_e32 v168, v168, v170
	v_mov_b32_e32 v170, v168
	s_nop 1
	v_permlane32_swap_b32_e32 v168, v170
	v_max_f32_e32 v168, v168, v170
	v_mov_b32_e32 v170, v168
	v_sub_f32_e32 v218, v218, v170
	v_sub_f32_e32 v219, v219, v170
	v_sub_f32_e32 v220, v220, v170
	v_sub_f32_e32 v221, v221, v170
	v_sub_f32_e32 v222, v222, v170
	v_sub_f32_e32 v223, v223, v170
	v_sub_f32_e32 v224, v224, v170
	v_sub_f32_e32 v225, v225, v170
	v_sub_f32_e32 v226, v226, v170
	v_sub_f32_e32 v227, v227, v170
	v_sub_f32_e32 v228, v228, v170
	v_sub_f32_e32 v229, v229, v170
	v_sub_f32_e32 v230, v230, v170
	v_sub_f32_e32 v231, v231, v170
	v_sub_f32_e32 v232, v232, v170
	v_sub_f32_e32 v233, v233, v170
	v_sub_f32_e32 v32, v32, v170
	v_sub_f32_e32 v33, v33, v170
	v_sub_f32_e32 v34, v34, v170
	v_sub_f32_e32 v35, v35, v170
	v_sub_f32_e32 v36, v36, v170
	v_sub_f32_e32 v37, v37, v170
	v_sub_f32_e32 v38, v38, v170
	v_sub_f32_e32 v39, v39, v170
	v_sub_f32_e32 v40, v40, v170
	v_sub_f32_e32 v41, v41, v170
	v_sub_f32_e32 v42, v42, v170
	v_sub_f32_e32 v43, v43, v170
	v_sub_f32_e32 v44, v44, v170
	v_sub_f32_e32 v45, v45, v170
	v_sub_f32_e32 v46, v46, v170
	v_sub_f32_e32 v47, v47, v170
	v_sub_f32_e32 v48, v48, v170
	v_sub_f32_e32 v49, v49, v170
	v_sub_f32_e32 v50, v50, v170
	v_sub_f32_e32 v51, v51, v170
	v_sub_f32_e32 v52, v52, v170
	v_sub_f32_e32 v53, v53, v170
	v_sub_f32_e32 v54, v54, v170
	v_sub_f32_e32 v55, v55, v170
	v_sub_f32_e32 v56, v56, v170
	v_sub_f32_e32 v57, v57, v170
	v_sub_f32_e32 v58, v58, v170
	v_sub_f32_e32 v59, v59, v170
	v_sub_f32_e32 v60, v60, v170
	v_sub_f32_e32 v61, v61, v170
	v_sub_f32_e32 v62, v62, v170
	v_sub_f32_e32 v63, v63, v170
	s_waitcnt lgkmcnt(3)
	v_mfma_f32_32x32x16_bf16 v[64:79], v[136:139], v[112:115], v[218:233]
	v_exp_f32_e32 v32, v32
	v_exp_f32_e32 v48, v48
	v_exp_f32_e32 v33, v33
	v_exp_f32_e32 v49, v49
	v_exp_f32_e32 v34, v34
	ds_read_b128 v[136:139], v243 offset:13376
	s_mov_b32 s55, s52
	s_mov_b32 s52, s53
	s_mov_b32 s53, s54
	s_mov_b32 s54, s55
	s_mov_b32 s9, 0
	s_waitcnt lgkmcnt(3)
	v_mfma_f32_32x32x16_bf16 v[80:95], v[140:143], v[112:115], v[218:233]
	v_exp_f32_e32 v50, v50
	v_cvt_pk_bf16_f32 v96, v32, v33
	v_cvt_pk_bf16_f32 v104, v48, v49
	v_exp_f32_e32 v35, v35
	v_exp_f32_e32 v51, v51
	ds_read_b128 v[140:143], v243 offset:20032
	global_load_dwordx4 v[208:211], v167, s[2:3]
	global_load_dwordx2 v[216:217], v165, s[10:11]
	global_load_dwordx4 v[212:215], v167, s[4:5]
	s_add_u32 s2, s2, 0x2000
	s_addc_u32 s3, s3, 0
	s_add_u32 s10, s10, 0x1000
	s_addc_u32 s11, s11, 0
	s_add_u32 s4, s4, 0x2000
	s_addc_u32 s5, s5, 0
	v_add_u32_e32 v163, s53, v240
	v_add_u32_e32 v164, s54, v241
	s_waitcnt lgkmcnt(3)
	v_mfma_f32_32x32x16_bf16 v[64:79], v[144:147], v[116:119], v[64:79]
	v_exp_f32_e32 v36, v36
	v_exp_f32_e32 v52, v52
	v_cvt_pk_bf16_f32 v97, v34, v35
	v_cvt_pk_bf16_f32 v105, v50, v51
	v_exp_f32_e32 v37, v37
	ds_read_b128 v[144:147], v243 offset:13408
	s_waitcnt lgkmcnt(3)
	v_mfma_f32_32x32x16_bf16 v[80:95], v[148:151], v[116:119], v[80:95]
	v_exp_f32_e32 v53, v53
	v_exp_f32_e32 v38, v38
	v_exp_f32_e32 v54, v54
	v_cvt_pk_bf16_f32 v98, v36, v37
	v_cvt_pk_bf16_f32 v106, v52, v53
	ds_read_b128 v[148:151], v243 offset:20064
	s_waitcnt lgkmcnt(3)
	v_mfma_f32_32x32x16_bf16 v[64:79], v[136:139], v[120:123], v[64:79]
	v_exp_f32_e32 v39, v39
	v_exp_f32_e32 v55, v55
	v_exp_f32_e32 v40, v40
	v_exp_f32_e32 v56, v56
	v_cvt_pk_bf16_f32 v99, v38, v39
	ds_read_b128 v[136:139], v243 offset:13440
	s_waitcnt lgkmcnt(3)
	v_mfma_f32_32x32x16_bf16 v[80:95], v[140:143], v[120:123], v[80:95]
	v_cvt_pk_bf16_f32 v107, v54, v55
	v_exp_f32_e32 v41, v41
	v_exp_f32_e32 v57, v57
	v_exp_f32_e32 v42, v42
	v_exp_f32_e32 v58, v58
	ds_read_b128 v[140:143], v243 offset:20096
	s_waitcnt lgkmcnt(3)
	v_mfma_f32_32x32x16_bf16 v[64:79], v[144:147], v[124:127], v[64:79]
	v_cvt_pk_bf16_f32 v100, v40, v41
	v_cvt_pk_bf16_f32 v108, v56, v57
	v_exp_f32_e32 v43, v43
	v_exp_f32_e32 v59, v59
	v_exp_f32_e32 v44, v44
	ds_read_b128 v[144:147], v243 offset:13472
	ds_read_b64_tr_b16 v[176:177], v163 offset:0
	ds_read_b64_tr_b16 v[178:179], v163 offset:1536
	s_waitcnt vmcnt(5)
	ds_write_b128 v238, v[152:155]
	s_waitcnt vmcnt(4)
	ds_write_b64 v239, v[160:161]
	s_waitcnt vmcnt(3)
	ds_write_b128 v164, v[156:159]
	s_waitcnt lgkmcnt(8)
	v_mfma_f32_32x32x16_bf16 v[80:95], v[148:151], v[124:127], v[80:95]
	v_exp_f32_e32 v60, v60
	v_cvt_pk_bf16_f32 v101, v42, v43
	v_cvt_pk_bf16_f32 v109, v58, v59
	v_exp_f32_e32 v45, v45
	v_exp_f32_e32 v61, v61
	ds_read_b128 v[148:151], v243 offset:20128
	ds_read_b64_tr_b16 v[180:181], v163 offset:64
	ds_read_b64_tr_b16 v[182:183], v163 offset:1600
	s_waitcnt lgkmcnt(10)
	v_mfma_f32_32x32x16_bf16 v[64:79], v[136:139], v[128:131], v[64:79]
	v_exp_f32_e32 v46, v46
	v_exp_f32_e32 v62, v62
	v_cvt_pk_bf16_f32 v102, v44, v45
	v_cvt_pk_bf16_f32 v110, v60, v61
	v_exp_f32_e32 v47, v47
	v_exp_f32_e32 v63, v63
	ds_read_b64_tr_b16 v[184:185], v163 offset:6144
	ds_read_b64_tr_b16 v[186:187], v163 offset:7680
	s_waitcnt lgkmcnt(11)
	v_mfma_f32_32x32x16_bf16 v[80:95], v[140:143], v[128:131], v[80:95]
	v_cvt_pk_bf16_f32 v103, v46, v47
	v_cvt_pk_bf16_f32 v111, v62, v63
	ds_read_b64_tr_b16 v[188:189], v163 offset:6208
	ds_read_b64_tr_b16 v[190:191], v163 offset:7744
	s_waitcnt lgkmcnt(12)
	v_mfma_f32_32x32x16_bf16 v[64:79], v[144:147], v[132:135], v[64:79]
	s_waitcnt lgkmcnt(6)
	v_mfma_f32_32x32x16_bf16 v[80:95], v[148:151], v[132:135], v[80:95]
	s_nop 13
	s_waitcnt lgkmcnt(0)
	s_barrier
	s_cmp_eq_u32 s7, 0
	s_cbranch_scc1 .Lamla_tail
	.p2alignl 6, 3212836864

; #define AT_STEP(SC0, SC1, SN0, SN1, t, DOK, DOV) do { \
;             if (DOK) AT_GLOADK(((t) + 2) * 64); \
;             if (DOV) { AT_GLOADV(((t) + 1) * 64); AT_QK(SN0, SN1, ((t) + 1) & 1); } \
;             AT_SMPV(SC0, SC1, (t) & 1); \
;             if (DOK) AT_WRITEK((t) & 1); \
;             if (DOV) AT_WRITEV(((t) + 1) & 1); \
;             __syncthreads(); } while (0)
; template <bool MLA>
; DI void attn_phase(const int TID, const int BID, LAS unsigned char* lds, const Params& p, bool need_ctx) {
;     ...
;         AT_QK(sa0, sa1, 0);
;         __syncthreads();
;         int t = 0;
;         for (; t < ntile - 2; t += 2) {
;             AT_STEP(sa0, sa1, sb0, sb1, t, true, true);
;             AT_STEP(sb0, sb1, sa0, sa1, t + 1, true, true);
;         }
.Lagqa_prio:
	ds_read_b128 v[136:139], v243 offset:0
	ds_read_b128 v[140:143], v243 offset:4608
	ds_read_b128 v[144:147], v243 offset:32
	ds_read_b128 v[148:151], v243 offset:4640
	s_waitcnt lgkmcnt(3)
	v_mfma_f32_32x32x16_bf16 v[32:47], v[136:139], v[112:115], 0
	ds_read_b128 v[136:139], v243 offset:64
	s_waitcnt lgkmcnt(3)
	v_mfma_f32_32x32x16_bf16 v[48:63], v[140:143], v[112:115], 0
	ds_read_b128 v[140:143], v243 offset:4672
	s_waitcnt lgkmcnt(3)
	v_mfma_f32_32x32x16_bf16 v[32:47], v[144:147], v[116:119], v[32:47]
	ds_read_b128 v[144:147], v243 offset:96
	s_waitcnt lgkmcnt(3)
	v_mfma_f32_32x32x16_bf16 v[48:63], v[148:151], v[116:119], v[48:63]
	ds_read_b128 v[148:151], v243 offset:4704
	s_waitcnt lgkmcnt(3)
	v_mfma_f32_32x32x16_bf16 v[32:47], v[136:139], v[120:123], v[32:47]
	s_waitcnt lgkmcnt(2)
	v_mfma_f32_32x32x16_bf16 v[48:63], v[140:143], v[120:123], v[48:63]
	s_waitcnt lgkmcnt(1)
	v_mfma_f32_32x32x16_bf16 v[32:47], v[144:147], v[124:127], v[32:47]
	s_waitcnt lgkmcnt(0)
	v_mfma_f32_32x32x16_bf16 v[48:63], v[148:151], v[124:127], v[48:63]
	s_waitcnt lgkmcnt(0)
	s_nop 7
	s_barrier
	ds_read_b128 v[136:139], v243 offset:9216
	ds_read_b128 v[140:143], v243 offset:13824
	ds_read_b128 v[144:147], v243 offset:9248
	ds_read_b128 v[148:151], v243 offset:13856
	v_max3_f32 v168, v32, v33, v34
	v_max3_f32 v170, v48, v49, v50
	v_max3_f32 v168, v168, v35, v36
	v_max3_f32 v170, v170, v51, v52
	v_max3_f32 v168, v168, v37, v38
	v_max3_f32 v170, v170, v53, v54
	v_max3_f32 v168, v168, v39, v40
	v_max3_f32 v170, v170, v55, v56
	v_max3_f32 v168, v168, v41, v42
	v_max3_f32 v170, v170, v57, v58
	v_max3_f32 v168, v168, v43, v44
	v_max3_f32 v170, v170, v59, v60
	v_max3_f32 v168, v168, v45, v46
	v_max3_f32 v170, v170, v61, v62
	v_max_f32_e32 v168, v168, v47
	v_max_f32_e32 v170, v170, v63
	v_max_f32_e32 v168, v168, v170
	v_mov_b32_e32 v170, v168
	s_nop 1
	v_permlane32_swap_b32_e32 v168, v170
	v_max_f32_e32 v168, v168, v170
	v_mov_b32_e32 v170, v168
	v_sub_f32_e32 v218, v218, v170
	v_sub_f32_e32 v219, v219, v170
	v_sub_f32_e32 v220, v220, v170
	v_sub_f32_e32 v221, v221, v170
	v_sub_f32_e32 v222, v222, v170
	v_sub_f32_e32 v223, v223, v170
	v_sub_f32_e32 v224, v224, v170
	v_sub_f32_e32 v225, v225, v170
	v_sub_f32_e32 v226, v226, v170
	v_sub_f32_e32 v227, v227, v170
	v_sub_f32_e32 v228, v228, v170
	v_sub_f32_e32 v229, v229, v170
	v_sub_f32_e32 v230, v230, v170
	v_sub_f32_e32 v231, v231, v170
	v_sub_f32_e32 v232, v232, v170
	v_sub_f32_e32 v233, v233, v170
	v_sub_f32_e32 v32, v32, v170
	v_sub_f32_e32 v33, v33, v170
	v_sub_f32_e32 v34, v34, v170
	v_sub_f32_e32 v35, v35, v170
	v_sub_f32_e32 v36, v36, v170
	v_sub_f32_e32 v37, v37, v170
	v_sub_f32_e32 v38, v38, v170
	v_sub_f32_e32 v39, v39, v170
	v_sub_f32_e32 v40, v40, v170
	v_sub_f32_e32 v41, v41, v170
	v_sub_f32_e32 v42, v42, v170
	v_sub_f32_e32 v43, v43, v170
	v_sub_f32_e32 v44, v44, v170
	v_sub_f32_e32 v45, v45, v170
	v_sub_f32_e32 v46, v46, v170
	v_sub_f32_e32 v47, v47, v170
	v_sub_f32_e32 v48, v48, v170
	v_sub_f32_e32 v49, v49, v170
	v_sub_f32_e32 v50, v50, v170
	v_sub_f32_e32 v51, v51, v170
	v_sub_f32_e32 v52, v52, v170
	v_sub_f32_e32 v53, v53, v170
	v_sub_f32_e32 v54, v54, v170
	v_sub_f32_e32 v55, v55, v170
	v_sub_f32_e32 v56, v56, v170
	v_sub_f32_e32 v57, v57, v170
	v_sub_f32_e32 v58, v58, v170
	v_sub_f32_e32 v59, v59, v170
	v_sub_f32_e32 v60, v60, v170
	v_sub_f32_e32 v61, v61, v170
	v_sub_f32_e32 v62, v62, v170
	v_sub_f32_e32 v63, v63, v170
	s_waitcnt lgkmcnt(3)
	v_mfma_f32_32x32x16_bf16 v[64:79], v[136:139], v[112:115], v[218:233]
	v_exp_f32_e32 v32, v32
	v_exp_f32_e32 v48, v48
	v_exp_f32_e32 v33, v33
	v_exp_f32_e32 v49, v49
	v_exp_f32_e32 v34, v34
	v_exp_f32_e32 v50, v50
	v_cvt_pk_bf16_f32 v96, v32, v33
	ds_read_b128 v[136:139], v243 offset:9280
	s_mov_b32 s55, s52
	s_mov_b32 s52, s53
	s_mov_b32 s53, s54
	s_mov_b32 s54, s55
	s_mov_b32 s9, 0
	s_waitcnt lgkmcnt(3)
	v_mfma_f32_32x32x16_bf16 v[80:95], v[140:143], v[112:115], v[218:233]
	v_cvt_pk_bf16_f32 v104, v48, v49
	v_exp_f32_e32 v35, v35
	v_exp_f32_e32 v51, v51
	v_exp_f32_e32 v36, v36
	v_exp_f32_e32 v52, v52
	v_cvt_pk_bf16_f32 v97, v34, v35
	v_cvt_pk_bf16_f32 v105, v50, v51
	v_exp_f32_e32 v37, v37
	ds_read_b128 v[140:143], v243 offset:13888
	global_load_dwordx4 v[208:211], v167, s[2:3]
	global_load_dwordx4 v[212:215], v167, s[4:5]
	s_add_u32 s2, s2, 0x2000
	s_addc_u32 s3, s3, 0
	s_add_u32 s4, s4, 0x2000
	s_addc_u32 s5, s5, 0
	v_add_u32_e32 v163, s53, v240
	v_add_u32_e32 v164, s54, v241
	s_waitcnt lgkmcnt(3)
	v_mfma_f32_32x32x16_bf16 v[64:79], v[144:147], v[116:119], v[64:79]
	v_exp_f32_e32 v53, v53
	v_exp_f32_e32 v38, v38
	v_exp_f32_e32 v54, v54
	v_cvt_pk_bf16_f32 v98, v36, v37
	v_cvt_pk_bf16_f32 v106, v52, v53
	v_exp_f32_e32 v39, v39
	v_exp_f32_e32 v55, v55
	v_exp_f32_e32 v40, v40
	ds_read_b128 v[144:147], v243 offset:9312
	ds_read_b64_tr_b16 v[176:177], v163 offset:0
	ds_read_b64_tr_b16 v[178:179], v163 offset:1536
	s_waitcnt lgkmcnt(5)
	v_mfma_f32_32x32x16_bf16 v[80:95], v[148:151], v[116:119], v[80:95]
	v_exp_f32_e32 v56, v56
	v_cvt_pk_bf16_f32 v99, v38, v39
	v_cvt_pk_bf16_f32 v107, v54, v55
	v_exp_f32_e32 v41, v41
	v_exp_f32_e32 v57, v57
	v_exp_f32_e32 v42, v42
	v_exp_f32_e32 v58, v58
	ds_read_b128 v[148:151], v243 offset:13920
	ds_read_b64_tr_b16 v[180:181], v163 offset:64
	ds_read_b64_tr_b16 v[182:183], v163 offset:1600
	s_waitcnt lgkmcnt(7)
	v_mfma_f32_32x32x16_bf16 v[64:79], v[136:139], v[120:123], v[64:79]
	v_cvt_pk_bf16_f32 v100, v40, v41
	v_cvt_pk_bf16_f32 v108, v56, v57
	v_exp_f32_e32 v43, v43
	v_exp_f32_e32 v59, v59
	v_exp_f32_e32 v44, v44
	v_exp_f32_e32 v60, v60
	v_cvt_pk_bf16_f32 v101, v42, v43
	v_cvt_pk_bf16_f32 v109, v58, v59
	ds_read_b64_tr_b16 v[184:185], v163 offset:6144
	ds_read_b64_tr_b16 v[186:187], v163 offset:7680
	s_waitcnt vmcnt(3)
	ds_write_b128 v238, v[152:155]
	s_waitcnt vmcnt(2)
	ds_write_b128 v164, v[156:159]
	s_waitcnt lgkmcnt(10)
	v_mfma_f32_32x32x16_bf16 v[80:95], v[140:143], v[120:123], v[80:95]
	v_exp_f32_e32 v45, v45
	v_exp_f32_e32 v61, v61
	v_exp_f32_e32 v46, v46
	v_exp_f32_e32 v62, v62
	v_cvt_pk_bf16_f32 v102, v44, v45
	v_cvt_pk_bf16_f32 v110, v60, v61
	v_exp_f32_e32 v47, v47
	v_exp_f32_e32 v63, v63
	ds_read_b64_tr_b16 v[188:189], v163 offset:6208
	ds_read_b64_tr_b16 v[190:191], v163 offset:7744
	s_waitcnt lgkmcnt(11)
	v_mfma_f32_32x32x16_bf16 v[64:79], v[144:147], v[124:127], v[64:79]
	v_cvt_pk_bf16_f32 v103, v46, v47
	v_cvt_pk_bf16_f32 v111, v62, v63
	s_waitcnt lgkmcnt(8)
	v_mfma_f32_32x32x16_bf16 v[80:95], v[148:151], v[124:127], v[80:95]
	s_nop 13
	s_waitcnt lgkmcnt(2)
	s_waitcnt lgkmcnt(0)
	s_barrier
	s_cmp_eq_u32 s7, 0
	s_cbranch_scc1 .Lagqa_tail
	.p2alignl 6, 3212836864

; template <class Epi>
; DI void gemm_phase(const int TID, const int BID, LAS unsigned char* lds, const Gemm g, const Epi& E) {
;     ...
;         if (!has_next) break;
; #pragma unroll
;         for (int a = 0; a < 2; ++a)
; #pragma unroll
;             for (int b = 0; b < 2; ++b)
; #pragma unroll
;                 for (int m = 0; m < 4; ++m)
; #pragma unroll
;                     for (int n = 0; n < 2; ++n) acc[a][b][m][n] = (f32x4){0.f, 0.f, 0.f, 0.f};
;         cur = nxt; cA = nA; cB = nB; ++ui;
.LBB0_357:
	v_mov_b32_e32 v127, 0
	s_andn2_b64 vcc, exec, s[48:49]
	v_mov_b32_e32 v126, v127
	v_mov_b32_e32 v125, v127
	v_mov_b32_e32 v124, v127
	v_mov_b32_e32 v123, v127
	v_mov_b32_e32 v122, v127
	v_mov_b32_e32 v121, v127
	v_mov_b32_e32 v120, v127
	v_mov_b32_e32 v111, v127
	v_mov_b32_e32 v110, v127
	v_mov_b32_e32 v109, v127
	v_mov_b32_e32 v108, v127
	v_mov_b32_e32 v107, v127
	v_mov_b32_e32 v106, v127
	v_mov_b32_e32 v105, v127
	v_mov_b32_e32 v104, v127
	v_mov_b32_e32 v95, v127
	v_mov_b32_e32 v94, v127
	v_mov_b32_e32 v93, v127
	v_mov_b32_e32 v92, v127
	v_mov_b32_e32 v91, v127
	v_mov_b32_e32 v90, v127
	v_mov_b32_e32 v89, v127
	v_mov_b32_e32 v88, v127
	v_mov_b32_e32 v79, v127
	v_mov_b32_e32 v78, v127
	v_mov_b32_e32 v77, v127
	v_mov_b32_e32 v76, v127
	v_mov_b32_e32 v75, v127
	v_mov_b32_e32 v74, v127
	v_mov_b32_e32 v73, v127
	v_mov_b32_e32 v72, v127
	v_mov_b32_e32 v119, v127
	v_mov_b32_e32 v118, v127
	v_mov_b32_e32 v117, v127
	v_mov_b32_e32 v116, v127
	v_mov_b32_e32 v115, v127
	v_mov_b32_e32 v114, v127
	v_mov_b32_e32 v113, v127
	v_mov_b32_e32 v112, v127
	v_mov_b32_e32 v103, v127
	v_mov_b32_e32 v102, v127
	v_mov_b32_e32 v101, v127
	v_mov_b32_e32 v100, v127
	v_mov_b32_e32 v99, v127
	v_mov_b32_e32 v98, v127
	v_mov_b32_e32 v97, v127
	v_mov_b32_e32 v96, v127
	v_mov_b32_e32 v87, v127
	v_mov_b32_e32 v86, v127
	v_mov_b32_e32 v85, v127
	v_mov_b32_e32 v84, v127
	v_mov_b32_e32 v83, v127
	v_mov_b32_e32 v82, v127
	v_mov_b32_e32 v81, v127
	v_mov_b32_e32 v80, v127
	v_mov_b32_e32 v71, v127
	v_mov_b32_e32 v70, v127
	v_mov_b32_e32 v69, v127
	v_mov_b32_e32 v68, v127
	v_mov_b32_e32 v67, v127
	v_mov_b32_e32 v66, v127
	v_mov_b32_e32 v65, v127
	v_mov_b32_e32 v64, v127
	v_mov_b32_e32 v63, v127
	v_mov_b32_e32 v62, v127
	v_mov_b32_e32 v61, v127
	v_mov_b32_e32 v60, v127
	v_mov_b32_e32 v59, v127
	v_mov_b32_e32 v58, v127
	v_mov_b32_e32 v57, v127
	v_mov_b32_e32 v56, v127
	v_mov_b32_e32 v47, v127
	v_mov_b32_e32 v46, v127
	v_mov_b32_e32 v45, v127
	v_mov_b32_e32 v44, v127
	v_mov_b32_e32 v43, v127
	v_mov_b32_e32 v42, v127
	v_mov_b32_e32 v41, v127
	v_mov_b32_e32 v40, v127
	v_mov_b32_e32 v31, v127
	v_mov_b32_e32 v30, v127
	v_mov_b32_e32 v29, v127
	v_mov_b32_e32 v28, v127
	v_mov_b32_e32 v27, v127
	v_mov_b32_e32 v26, v127
	v_mov_b32_e32 v25, v127
	v_mov_b32_e32 v24, v127
	v_mov_b32_e32 v15, v127
	v_mov_b32_e32 v14, v127
	v_mov_b32_e32 v13, v127
	v_mov_b32_e32 v12, v127
	v_mov_b32_e32 v11, v127
	v_mov_b32_e32 v10, v127
	v_mov_b32_e32 v9, v127
	v_mov_b32_e32 v8, v127
	v_mov_b32_e32 v55, v127
	v_mov_b32_e32 v54, v127
	v_mov_b32_e32 v53, v127
	v_mov_b32_e32 v52, v127
	v_mov_b32_e32 v51, v127
	v_mov_b32_e32 v50, v127
	v_mov_b32_e32 v49, v127
	v_mov_b32_e32 v48, v127
	v_mov_b32_e32 v39, v127
	v_mov_b32_e32 v38, v127
	v_mov_b32_e32 v37, v127
	v_mov_b32_e32 v36, v127
	v_mov_b32_e32 v35, v127
	v_mov_b32_e32 v34, v127
	v_mov_b32_e32 v33, v127
	v_mov_b32_e32 v32, v127
	v_mov_b32_e32 v23, v127
	v_mov_b32_e32 v22, v127
	v_mov_b32_e32 v21, v127
	v_mov_b32_e32 v20, v127
	v_mov_b32_e32 v19, v127
	v_mov_b32_e32 v18, v127
	v_mov_b32_e32 v17, v127
	v_mov_b32_e32 v16, v127
	v_mov_b32_e32 v7, v127
	v_mov_b32_e32 v6, v127
	v_mov_b32_e32 v5, v127
	v_mov_b32_e32 v4, v127
	v_mov_b32_e32 v3, v127
	v_mov_b32_e32 v2, v127
	v_mov_b32_e32 v1, v127
	v_mov_b32_e32 v0, v127
	s_cbranch_vccnz .LBB0_360
	s_add_u32 s6, s6, 0x80
	s_addc_u32 s7, s7, 0
	s_add_u32 s12, s8, 0x100
	s_addc_u32 s13, s9, 0
	s_mov_b32 s8, 0
	.p2alignl 6, 3212836864

; template <class Epi>
; DI void gemm_phase(const int TID, const int BID, LAS unsigned char* lds, const Gemm g, const Epi& E) {
;     ...
;         if (!has_next) break;
; #pragma unroll
;         for (int a = 0; a < 2; ++a)
; #pragma unroll
;             for (int b = 0; b < 2; ++b)
; #pragma unroll
;                 for (int m = 0; m < 4; ++m)
; #pragma unroll
;                     for (int n = 0; n < 2; ++n) acc[a][b][m][n] = (f32x4){0.f, 0.f, 0.f, 0.f};
;         cur = nxt; cA = nA; cB = nB; ++ui;
.LBB0_489:
	v_mov_b32_e32 v127, 0
	s_andn2_b64 vcc, exec, s[10:11]
	v_mov_b32_e32 v126, v127
	v_mov_b32_e32 v125, v127
	v_mov_b32_e32 v124, v127
	v_mov_b32_e32 v123, v127
	v_mov_b32_e32 v122, v127
	v_mov_b32_e32 v121, v127
	v_mov_b32_e32 v120, v127
	v_mov_b32_e32 v111, v127
	v_mov_b32_e32 v110, v127
	v_mov_b32_e32 v109, v127
	v_mov_b32_e32 v108, v127
	v_mov_b32_e32 v107, v127
	v_mov_b32_e32 v106, v127
	v_mov_b32_e32 v105, v127
	v_mov_b32_e32 v104, v127
	v_mov_b32_e32 v95, v127
	v_mov_b32_e32 v94, v127
	v_mov_b32_e32 v93, v127
	v_mov_b32_e32 v92, v127
	v_mov_b32_e32 v91, v127
	v_mov_b32_e32 v90, v127
	v_mov_b32_e32 v89, v127
	v_mov_b32_e32 v88, v127
	v_mov_b32_e32 v79, v127
	v_mov_b32_e32 v78, v127
	v_mov_b32_e32 v77, v127
	v_mov_b32_e32 v76, v127
	v_mov_b32_e32 v75, v127
	v_mov_b32_e32 v74, v127
	v_mov_b32_e32 v73, v127
	v_mov_b32_e32 v72, v127
	v_mov_b32_e32 v119, v127
	v_mov_b32_e32 v118, v127
	v_mov_b32_e32 v117, v127
	v_mov_b32_e32 v116, v127
	v_mov_b32_e32 v115, v127
	v_mov_b32_e32 v114, v127
	v_mov_b32_e32 v113, v127
	v_mov_b32_e32 v112, v127
	v_mov_b32_e32 v103, v127
	v_mov_b32_e32 v102, v127
	v_mov_b32_e32 v101, v127
	v_mov_b32_e32 v100, v127
	v_mov_b32_e32 v99, v127
	v_mov_b32_e32 v98, v127
	v_mov_b32_e32 v97, v127
	v_mov_b32_e32 v96, v127
	v_mov_b32_e32 v87, v127
	v_mov_b32_e32 v86, v127
	v_mov_b32_e32 v85, v127
	v_mov_b32_e32 v84, v127
	v_mov_b32_e32 v83, v127
	v_mov_b32_e32 v82, v127
	v_mov_b32_e32 v81, v127
	v_mov_b32_e32 v80, v127
	v_mov_b32_e32 v71, v127
	v_mov_b32_e32 v70, v127
	v_mov_b32_e32 v69, v127
	v_mov_b32_e32 v68, v127
	v_mov_b32_e32 v67, v127
	v_mov_b32_e32 v66, v127
	v_mov_b32_e32 v65, v127
	v_mov_b32_e32 v64, v127
	v_mov_b32_e32 v63, v127
	v_mov_b32_e32 v62, v127
	v_mov_b32_e32 v61, v127
	v_mov_b32_e32 v60, v127
	v_mov_b32_e32 v59, v127
	v_mov_b32_e32 v58, v127
	v_mov_b32_e32 v57, v127
	v_mov_b32_e32 v56, v127
	v_mov_b32_e32 v47, v127
	v_mov_b32_e32 v46, v127
	v_mov_b32_e32 v45, v127
	v_mov_b32_e32 v44, v127
	v_mov_b32_e32 v43, v127
	v_mov_b32_e32 v42, v127
	v_mov_b32_e32 v41, v127
	v_mov_b32_e32 v40, v127
	v_mov_b32_e32 v31, v127
	v_mov_b32_e32 v30, v127
	v_mov_b32_e32 v29, v127
	v_mov_b32_e32 v28, v127
	v_mov_b32_e32 v27, v127
	v_mov_b32_e32 v26, v127
	v_mov_b32_e32 v25, v127
	v_mov_b32_e32 v24, v127
	v_mov_b32_e32 v15, v127
	v_mov_b32_e32 v14, v127
	v_mov_b32_e32 v13, v127
	v_mov_b32_e32 v12, v127
	v_mov_b32_e32 v11, v127
	v_mov_b32_e32 v10, v127
	v_mov_b32_e32 v9, v127
	v_mov_b32_e32 v8, v127
	v_mov_b32_e32 v55, v127
	v_mov_b32_e32 v54, v127
	v_mov_b32_e32 v53, v127
	v_mov_b32_e32 v52, v127
	v_mov_b32_e32 v51, v127
	v_mov_b32_e32 v50, v127
	v_mov_b32_e32 v49, v127
	v_mov_b32_e32 v48, v127
	v_mov_b32_e32 v39, v127
	v_mov_b32_e32 v38, v127
	v_mov_b32_e32 v37, v127
	v_mov_b32_e32 v36, v127
	v_mov_b32_e32 v35, v127
	v_mov_b32_e32 v34, v127
	v_mov_b32_e32 v33, v127
	v_mov_b32_e32 v32, v127
	v_mov_b32_e32 v23, v127
	v_mov_b32_e32 v22, v127
	v_mov_b32_e32 v21, v127
	v_mov_b32_e32 v20, v127
	v_mov_b32_e32 v19, v127
	v_mov_b32_e32 v18, v127
	v_mov_b32_e32 v17, v127
	v_mov_b32_e32 v16, v127
	v_mov_b32_e32 v7, v127
	v_mov_b32_e32 v6, v127
	v_mov_b32_e32 v5, v127
	v_mov_b32_e32 v4, v127
	v_mov_b32_e32 v3, v127
	v_mov_b32_e32 v2, v127
	v_mov_b32_e32 v1, v127
	v_mov_b32_e32 v0, v127
	s_cbranch_vccnz .LBB0_492
	s_add_u32 s4, s4, 0x80
	s_addc_u32 s5, s5, 0
	s_add_u32 vcc_lo, s60, 0x100
	s_addc_u32 vcc_hi, s61, 0
	s_mov_b32 s60, 0
	.p2alignl 6, 3212836864

; template <class Epi>
; DI void gemm_phase(const int TID, const int BID, LAS unsigned char* lds, const Gemm g, const Epi& E) {
;     ...
;         for (int t = 0; t < nt; t += 2) {
;             const bool last = (t == nt - 2);
;             const char* a1 = cA + (size_t)(t + 1) * kstep;
;             const char* a2 = last ? nA : cA + (size_t)(t + 2) * kstep; const char* b2 = last ? nB : cB + (size_t)(t + 2) * kstep;
;             const char* a3 = a2 + kstep; const char* b3 = b2 + kstep;
;     ...
;         if (!has_next) break;
; #pragma unroll
;         for (int a = 0; a < 2; ++a)
; #pragma unroll
;             for (int b = 0; b < 2; ++b)
; #pragma unroll
;                 for (int m = 0; m < 4; ++m)
; #pragma unroll
;                     for (int n = 0; n < 2; ++n) acc[a][b][m][n] = (f32x4){0.f, 0.f, 0.f, 0.f};
;         cur = nxt; cA = nA; cB = nB; ++ui;
.LBB0_567:
	s_add_u32 s4, s4, 0x80
	s_addc_u32 s5, s5, 0
	s_add_u32 s28, s56, 0x100
	v_mov_b32_e32 v0, 0
	s_addc_u32 s29, s57, 0
	v_mov_b32_e32 v1, v0
	v_mov_b32_e32 v2, v0
	v_mov_b32_e32 v3, v0
	v_mov_b32_e32 v4, v0
	v_mov_b32_e32 v5, v0
	v_mov_b32_e32 v6, v0
	v_mov_b32_e32 v7, v0
	v_mov_b32_e32 v8, v0
	v_mov_b32_e32 v9, v0
	v_mov_b32_e32 v10, v0
	v_mov_b32_e32 v11, v0
	v_mov_b32_e32 v12, v0
	v_mov_b32_e32 v13, v0
	v_mov_b32_e32 v14, v0
	v_mov_b32_e32 v15, v0
	v_mov_b32_e32 v16, v0
	v_mov_b32_e32 v17, v0
	v_mov_b32_e32 v18, v0
	v_mov_b32_e32 v19, v0
	v_mov_b32_e32 v20, v0
	v_mov_b32_e32 v21, v0
	v_mov_b32_e32 v22, v0
	v_mov_b32_e32 v23, v0
	v_mov_b32_e32 v24, v0
	v_mov_b32_e32 v25, v0
	v_mov_b32_e32 v26, v0
	v_mov_b32_e32 v27, v0
	v_mov_b32_e32 v28, v0
	v_mov_b32_e32 v29, v0
	v_mov_b32_e32 v30, v0
	v_mov_b32_e32 v31, v0
	v_mov_b32_e32 v64, v0
	v_mov_b32_e32 v65, v0
	v_mov_b32_e32 v66, v0
	v_mov_b32_e32 v67, v0
	v_mov_b32_e32 v68, v0
	v_mov_b32_e32 v69, v0
	v_mov_b32_e32 v70, v0
	v_mov_b32_e32 v71, v0
	v_mov_b32_e32 v72, v0
	v_mov_b32_e32 v73, v0
	v_mov_b32_e32 v74, v0
	v_mov_b32_e32 v75, v0
	v_mov_b32_e32 v76, v0
	v_mov_b32_e32 v77, v0
	v_mov_b32_e32 v78, v0
	v_mov_b32_e32 v79, v0
	v_mov_b32_e32 v80, v0
	v_mov_b32_e32 v81, v0
	v_mov_b32_e32 v82, v0
	v_mov_b32_e32 v83, v0
	v_mov_b32_e32 v84, v0
	v_mov_b32_e32 v85, v0
	v_mov_b32_e32 v86, v0
	v_mov_b32_e32 v87, v0
	v_mov_b32_e32 v88, v0
	v_mov_b32_e32 v89, v0
	v_mov_b32_e32 v90, v0
	v_mov_b32_e32 v91, v0
	v_mov_b32_e32 v92, v0
	v_mov_b32_e32 v93, v0
	v_mov_b32_e32 v94, v0
	v_mov_b32_e32 v95, v0
	v_mov_b32_e32 v32, v0
	v_mov_b32_e32 v33, v0
	v_mov_b32_e32 v34, v0
	v_mov_b32_e32 v35, v0
	v_mov_b32_e32 v36, v0
	v_mov_b32_e32 v37, v0
	v_mov_b32_e32 v38, v0
	v_mov_b32_e32 v39, v0
	v_mov_b32_e32 v40, v0
	v_mov_b32_e32 v41, v0
	v_mov_b32_e32 v42, v0
	v_mov_b32_e32 v43, v0
	v_mov_b32_e32 v44, v0
	v_mov_b32_e32 v45, v0
	v_mov_b32_e32 v46, v0
	v_mov_b32_e32 v47, v0
	v_mov_b32_e32 v48, v0
	v_mov_b32_e32 v49, v0
	v_mov_b32_e32 v50, v0
	v_mov_b32_e32 v51, v0
	v_mov_b32_e32 v52, v0
	v_mov_b32_e32 v53, v0
	v_mov_b32_e32 v54, v0
	v_mov_b32_e32 v55, v0
	v_mov_b32_e32 v60, v0
	v_mov_b32_e32 v61, v0
	v_mov_b32_e32 v62, v0
	v_mov_b32_e32 v63, v0
	v_mov_b32_e32 v56, v0
	v_mov_b32_e32 v57, v0
	v_mov_b32_e32 v58, v0
	v_mov_b32_e32 v59, v0
	v_mov_b32_e32 v96, v0
	v_mov_b32_e32 v97, v0
	v_mov_b32_e32 v98, v0
	v_mov_b32_e32 v99, v0
	v_mov_b32_e32 v100, v0
	v_mov_b32_e32 v101, v0
	v_mov_b32_e32 v102, v0
	v_mov_b32_e32 v103, v0
	v_mov_b32_e32 v104, v0
	v_mov_b32_e32 v105, v0
	v_mov_b32_e32 v106, v0
	v_mov_b32_e32 v107, v0
	v_mov_b32_e32 v108, v0
	v_mov_b32_e32 v109, v0
	v_mov_b32_e32 v110, v0
	v_mov_b32_e32 v111, v0
	v_mov_b32_e32 v112, v0
	v_mov_b32_e32 v113, v0
	v_mov_b32_e32 v114, v0
	v_mov_b32_e32 v115, v0
	v_mov_b32_e32 v116, v0
	v_mov_b32_e32 v117, v0
	v_mov_b32_e32 v118, v0
	v_mov_b32_e32 v119, v0
	v_mov_b32_e32 v120, v0
	v_mov_b32_e32 v121, v0
	v_mov_b32_e32 v122, v0
	v_mov_b32_e32 v123, v0
	v_mov_b32_e32 v124, v0
	v_mov_b32_e32 v125, v0
	v_mov_b32_e32 v126, v0
	v_mov_b32_e32 v127, v0
	.p2alignl 6, 3212836864

; template <class Epi>
; DI void gemm_phase(const int TID, const int BID, LAS unsigned char* lds, const Gemm g, const Epi& E) {
;     ...
;         for (int t = 0; t < nt; t += 2) {
;             const bool last = (t == nt - 2);
;             const char* a1 = cA + (size_t)(t + 1) * kstep;
;             const char* a2 = last ? nA : cA + (size_t)(t + 2) * kstep; const char* b2 = last ? nB : cB + (size_t)(t + 2) * kstep;
;             const char* a3 = a2 + kstep; const char* b3 = b2 + kstep;
;     ...
;         if (!has_next) break;
; #pragma unroll
;         for (int a = 0; a < 2; ++a)
; #pragma unroll
;             for (int b = 0; b < 2; ++b)
; #pragma unroll
;                 for (int m = 0; m < 4; ++m)
; #pragma unroll
;                     for (int n = 0; n < 2; ++n) acc[a][b][m][n] = (f32x4){0.f, 0.f, 0.f, 0.f};
;         cur = nxt; cA = nA; cB = nB; ++ui;
.LBB0_745:
	s_add_u32 s2, s2, 0x80
	s_addc_u32 s3, s3, 0
	s_add_u32 s19, s4, 0x100
	v_mov_b32_e32 v4, 0
	s_addc_u32 s20, s5, 0
	v_mov_b32_e32 v5, v4
	v_mov_b32_e32 v6, v4
	v_mov_b32_e32 v7, v4
	v_mov_b32_e32 v0, v4
	v_mov_b32_e32 v1, v4
	v_mov_b32_e32 v2, v4
	v_mov_b32_e32 v3, v4
	v_mov_b32_e32 v16, v4
	v_mov_b32_e32 v17, v4
	v_mov_b32_e32 v18, v4
	v_mov_b32_e32 v19, v4
	v_mov_b32_e32 v20, v4
	v_mov_b32_e32 v21, v4
	v_mov_b32_e32 v22, v4
	v_mov_b32_e32 v23, v4
	v_mov_b32_e32 v32, v4
	v_mov_b32_e32 v33, v4
	v_mov_b32_e32 v34, v4
	v_mov_b32_e32 v35, v4
	v_mov_b32_e32 v36, v4
	v_mov_b32_e32 v37, v4
	v_mov_b32_e32 v38, v4
	v_mov_b32_e32 v39, v4
	v_mov_b32_e32 v48, v4
	v_mov_b32_e32 v49, v4
	v_mov_b32_e32 v50, v4
	v_mov_b32_e32 v51, v4
	v_mov_b32_e32 v52, v4
	v_mov_b32_e32 v53, v4
	v_mov_b32_e32 v54, v4
	v_mov_b32_e32 v55, v4
	v_mov_b32_e32 v8, v4
	v_mov_b32_e32 v9, v4
	v_mov_b32_e32 v10, v4
	v_mov_b32_e32 v11, v4
	v_mov_b32_e32 v12, v4
	v_mov_b32_e32 v13, v4
	v_mov_b32_e32 v14, v4
	v_mov_b32_e32 v15, v4
	v_mov_b32_e32 v24, v4
	v_mov_b32_e32 v25, v4
	v_mov_b32_e32 v26, v4
	v_mov_b32_e32 v27, v4
	v_mov_b32_e32 v28, v4
	v_mov_b32_e32 v29, v4
	v_mov_b32_e32 v30, v4
	v_mov_b32_e32 v31, v4
	v_mov_b32_e32 v40, v4
	v_mov_b32_e32 v41, v4
	v_mov_b32_e32 v42, v4
	v_mov_b32_e32 v43, v4
	v_mov_b32_e32 v44, v4
	v_mov_b32_e32 v45, v4
	v_mov_b32_e32 v46, v4
	v_mov_b32_e32 v47, v4
	v_mov_b32_e32 v56, v4
	v_mov_b32_e32 v57, v4
	v_mov_b32_e32 v58, v4
	v_mov_b32_e32 v59, v4
	v_mov_b32_e32 v60, v4
	v_mov_b32_e32 v61, v4
	v_mov_b32_e32 v62, v4
	v_mov_b32_e32 v63, v4
	v_mov_b32_e32 v80, v4
	v_mov_b32_e32 v81, v4
	v_mov_b32_e32 v82, v4
	v_mov_b32_e32 v83, v4
	v_mov_b32_e32 v84, v4
	v_mov_b32_e32 v85, v4
	v_mov_b32_e32 v86, v4
	v_mov_b32_e32 v87, v4
	v_mov_b32_e32 v96, v4
	v_mov_b32_e32 v97, v4
	v_mov_b32_e32 v98, v4
	v_mov_b32_e32 v99, v4
	v_mov_b32_e32 v100, v4
	v_mov_b32_e32 v101, v4
	v_mov_b32_e32 v102, v4
	v_mov_b32_e32 v103, v4
	v_mov_b32_e32 v112, v4
	v_mov_b32_e32 v113, v4
	v_mov_b32_e32 v114, v4
	v_mov_b32_e32 v115, v4
	v_mov_b32_e32 v116, v4
	v_mov_b32_e32 v117, v4
	v_mov_b32_e32 v118, v4
	v_mov_b32_e32 v119, v4
	v_mov_b32_e32 v128, v4
	v_mov_b32_e32 v129, v4
	v_mov_b32_e32 v130, v4
	v_mov_b32_e32 v131, v4
	v_mov_b32_e32 v132, v4
	v_mov_b32_e32 v133, v4
	v_mov_b32_e32 v134, v4
	v_mov_b32_e32 v135, v4
	v_mov_b32_e32 v88, v4
	v_mov_b32_e32 v89, v4
	v_mov_b32_e32 v90, v4
	v_mov_b32_e32 v91, v4
	v_mov_b32_e32 v92, v4
	v_mov_b32_e32 v93, v4
	v_mov_b32_e32 v94, v4
	v_mov_b32_e32 v95, v4
	v_mov_b32_e32 v104, v4
	v_mov_b32_e32 v105, v4
	v_mov_b32_e32 v106, v4
	v_mov_b32_e32 v107, v4
	v_mov_b32_e32 v108, v4
	v_mov_b32_e32 v109, v4
	v_mov_b32_e32 v110, v4
	v_mov_b32_e32 v111, v4
	v_mov_b32_e32 v120, v4
	v_mov_b32_e32 v121, v4
	v_mov_b32_e32 v122, v4
	v_mov_b32_e32 v123, v4
	v_mov_b32_e32 v124, v4
	v_mov_b32_e32 v125, v4
	v_mov_b32_e32 v126, v4
	v_mov_b32_e32 v127, v4
	v_mov_b32_e32 v136, v4
	v_mov_b32_e32 v137, v4
	v_mov_b32_e32 v138, v4
	v_mov_b32_e32 v139, v4
	v_mov_b32_e32 v140, v4
	v_mov_b32_e32 v141, v4
	v_mov_b32_e32 v142, v4
	v_mov_b32_e32 v143, v4
	.p2alignl 6, 3212836864
